# out-proj / FF2 residual epilogue loads (Xin, PLE) marked nt
# baseline (speedup 1.0000x reference)
.LBB0_1167:
	v_mbcnt_lo_u32_b32 v130, -1, 0
	v_mbcnt_hi_u32_b32 v130, -1, v130
	s_lshl_b32 s21, s55, 8
	v_ashrrev_i32_e32 v128, 1, v130
	v_and_b32_e32 v128, -8, v128
	s_or_b32 s21, s21, s50
	v_add_u32_e32 v128, s21, v128
	s_lshl_b32 s21, s28, 8
	v_ashrrev_i32_e32 v129, 31, v128
	s_add_i32 s21, s21, s49
	v_lshlrev_b64 v[154:155], 2, v[128:129]
	v_and_or_b32 v172, v130, 15, s21
	v_lshl_add_u64 v[128:129], s[10:11], 0, v[154:155]
	v_ashrrev_i32_e32 v173, 31, v172
	global_load_dwordx4 v[156:159], v[128:129], off nt
	global_load_dwordx4 v[160:163], v[128:129], off offset:16 nt
	global_load_dwordx4 v[176:179], v[128:129], off offset:512 nt
	global_load_dwordx4 v[180:183], v[128:129], off offset:528 nt
	v_lshl_add_u64 v[128:129], v[172:173], 3, s[16:17]
	v_lshlrev_b64 v[164:165], 12, v[172:173]
	global_load_dwordx2 v[216:217], v[128:129], off
	v_lshl_add_u64 v[128:129], s[8:9], 0, v[164:165]
	v_lshl_add_u64 v[128:129], v[128:129], 0, v[154:155]
	global_load_dwordx4 v[184:187], v[128:129], off nt
	global_load_dwordx4 v[188:191], v[128:129], off offset:16 nt
	global_load_dwordx4 v[192:195], v[128:129], off offset:512 nt
	global_load_dwordx4 v[196:199], v[128:129], off offset:528 nt
	v_or_b32_e32 v130, 16, v172
	v_lshl_add_u64 v[128:129], s[12:13], 0, v[154:155]
	v_ashrrev_i32_e32 v131, 31, v130
	global_load_dwordx4 v[140:143], v[128:129], off nt
	global_load_dwordx4 v[136:139], v[128:129], off offset:16 nt
	global_load_dwordx4 v[132:135], v[128:129], off offset:512 nt
	v_lshl_add_u64 v[166:167], v[130:131], 3, s[16:17]
	v_lshlrev_b64 v[218:219], 12, v[130:131]
	global_load_dwordx4 v[128:131], v[128:129], off offset:528 nt
	s_nop 0
	global_load_dwordx2 v[220:221], v[166:167], off
	v_lshl_add_u64 v[166:167], s[8:9], 0, v[218:219]
	v_lshl_add_u64 v[166:167], v[166:167], 0, v[154:155]
	global_load_dwordx4 v[200:203], v[166:167], off nt
	global_load_dwordx4 v[204:207], v[166:167], off offset:16 nt
	global_load_dwordx4 v[208:211], v[166:167], off offset:512 nt
	global_load_dwordx4 v[212:215], v[166:167], off offset:528 nt
	v_lshl_add_u64 v[164:165], s[6:7], 0, v[164:165]
	s_mov_b32 s28, 0x3fb504f3
	v_lshl_add_u64 v[222:223], v[164:165], 0, v[154:155]
	s_andn2_b64 vcc, exec, s[4:5]
	s_mov_b64 s[4:5], -1
	s_waitcnt vmcnt(0) lgkmcnt(0)
	v_pk_mul_f32 v[168:169], v[158:159], s[28:29] op_sel_hi:[1,0]
	v_pk_mul_f32 v[164:165], v[162:163], s[28:29] op_sel_hi:[1,0]
	v_pk_mul_f32 v[166:167], v[160:161], s[28:29] op_sel_hi:[1,0]
	v_pk_mul_f32 v[160:161], v[178:179], s[28:29] op_sel_hi:[1,0]
	v_pk_mul_f32 v[162:163], v[176:177], s[28:29] op_sel_hi:[1,0]
	v_pk_mul_f32 v[170:171], v[156:157], s[28:29] op_sel_hi:[1,0]
	v_sub_f32_e32 v177, v187, v216
	v_sub_f32_e32 v176, v186, v216
	v_sub_f32_e32 v179, v185, v216
	v_sub_f32_e32 v178, v184, v216
	v_pk_mul_f32 v[156:157], v[182:183], s[28:29] op_sel_hi:[1,0]
	v_pk_mul_f32 v[158:159], v[180:181], s[28:29] op_sel_hi:[1,0]
	v_sub_f32_e32 v181, v191, v216
	v_sub_f32_e32 v180, v190, v216
	v_sub_f32_e32 v183, v189, v216
	v_sub_f32_e32 v182, v188, v216
	v_sub_f32_e32 v185, v195, v216
	v_sub_f32_e32 v184, v194, v216
	v_sub_f32_e32 v187, v193, v216
	v_sub_f32_e32 v186, v192, v216
	v_sub_f32_e32 v189, v199, v216
	v_sub_f32_e32 v188, v198, v216
	v_sub_f32_e32 v191, v197, v216
	v_sub_f32_e32 v190, v196, v216
	v_pk_mul_f32 v[178:179], v[216:217], v[178:179] op_sel:[1,0]
	v_pk_mul_f32 v[176:177], v[216:217], v[176:177] op_sel:[1,0]
	v_pk_mul_f32 v[182:183], v[216:217], v[182:183] op_sel:[1,0]
	v_pk_mul_f32 v[180:181], v[216:217], v[180:181] op_sel:[1,0]
	v_pk_mul_f32 v[186:187], v[216:217], v[186:187] op_sel:[1,0]
	v_pk_mul_f32 v[184:185], v[216:217], v[184:185] op_sel:[1,0]
	v_pk_mul_f32 v[190:191], v[216:217], v[190:191] op_sel:[1,0]
	v_pk_mul_f32 v[188:189], v[216:217], v[188:189] op_sel:[1,0]
	v_pk_fma_f32 v[126:127], v[168:169], v[176:177], v[126:127]
	v_pk_fma_f32 v[124:125], v[170:171], v[178:179], v[124:125]
	v_pk_fma_f32 v[122:123], v[164:165], v[180:181], v[122:123]
	v_pk_fma_f32 v[120:121], v[166:167], v[182:183], v[120:121]
	v_pk_fma_f32 v[176:177], v[160:161], v[184:185], v[118:119]
	v_pk_fma_f32 v[178:179], v[162:163], v[186:187], v[116:117]
	v_pk_fma_f32 v[180:181], v[156:157], v[188:189], v[114:115]
	v_pk_fma_f32 v[182:183], v[158:159], v[190:191], v[112:113]
	v_pk_fma_f32 v[114:115], v[142:143], s[28:29], v[126:127] op_sel_hi:[1,0,1]
	v_pk_fma_f32 v[112:113], v[140:141], s[28:29], v[124:125] op_sel_hi:[1,0,1]
	v_pk_fma_f32 v[118:119], v[138:139], s[28:29], v[122:123] op_sel_hi:[1,0,1]
	v_pk_fma_f32 v[116:117], v[136:137], s[28:29], v[120:121] op_sel_hi:[1,0,1]
	v_pk_fma_f32 v[122:123], v[134:135], s[28:29], v[176:177] op_sel_hi:[1,0,1]
	v_pk_fma_f32 v[120:121], v[132:133], s[28:29], v[178:179] op_sel_hi:[1,0,1]
	global_store_dwordx4 v[222:223], v[112:115], off
	global_store_dwordx4 v[222:223], v[116:119], off offset:16
	s_nop 0
	v_pk_fma_f32 v[112:113], v[128:129], s[28:29], v[182:183] op_sel_hi:[1,0,1]
	v_pk_fma_f32 v[114:115], v[130:131], s[28:29], v[180:181] op_sel_hi:[1,0,1]
	global_store_dwordx4 v[222:223], v[120:123], off offset:512
	global_store_dwordx4 v[222:223], v[112:115], off offset:528
	s_nop 1
	v_sub_f32_e32 v113, v203, v220
	v_sub_f32_e32 v112, v202, v220
	v_sub_f32_e32 v115, v201, v220
	v_sub_f32_e32 v114, v200, v220
	v_pk_mul_f32 v[112:113], v[220:221], v[112:113] op_sel:[1,0]
	v_pk_mul_f32 v[114:115], v[220:221], v[114:115] op_sel:[1,0]
	v_pk_fma_f32 v[110:111], v[168:169], v[112:113], v[110:111]
	v_sub_f32_e32 v113, v207, v220
	v_sub_f32_e32 v112, v206, v220
	v_pk_fma_f32 v[108:109], v[170:171], v[114:115], v[108:109]
	v_sub_f32_e32 v115, v205, v220
	v_sub_f32_e32 v114, v204, v220
	v_pk_mul_f32 v[112:113], v[220:221], v[112:113] op_sel:[1,0]
	v_pk_mul_f32 v[114:115], v[220:221], v[114:115] op_sel:[1,0]
	v_pk_fma_f32 v[106:107], v[164:165], v[112:113], v[106:107]
	v_lshl_add_u64 v[112:113], s[6:7], 0, v[218:219]
	v_pk_fma_f32 v[110:111], v[142:143], s[28:29], v[110:111] op_sel_hi:[1,0,1]
	v_pk_fma_f32 v[108:109], v[140:141], s[28:29], v[108:109] op_sel_hi:[1,0,1]
	v_pk_fma_f32 v[104:105], v[166:167], v[114:115], v[104:105]
	v_pk_fma_f32 v[106:107], v[138:139], s[28:29], v[106:107] op_sel_hi:[1,0,1]
	v_lshl_add_u64 v[112:113], v[112:113], 0, v[154:155]
	v_pk_fma_f32 v[104:105], v[136:137], s[28:29], v[104:105] op_sel_hi:[1,0,1]
	global_store_dwordx4 v[112:113], v[108:111], off
	global_store_dwordx4 v[112:113], v[104:107], off offset:16
	s_nop 1
	v_sub_f32_e32 v107, v209, v220
	v_sub_f32_e32 v106, v208, v220
	v_sub_f32_e32 v105, v211, v220
	v_sub_f32_e32 v104, v210, v220
	v_pk_mul_f32 v[106:107], v[220:221], v[106:107] op_sel:[1,0]
	v_pk_mul_f32 v[104:105], v[220:221], v[104:105] op_sel:[1,0]
	v_pk_fma_f32 v[100:101], v[162:163], v[106:107], v[100:101]
	v_sub_f32_e32 v107, v213, v220
	v_sub_f32_e32 v106, v212, v220
	v_pk_fma_f32 v[102:103], v[160:161], v[104:105], v[102:103]
	v_sub_f32_e32 v105, v215, v220
	v_sub_f32_e32 v104, v214, v220
	v_pk_mul_f32 v[106:107], v[220:221], v[106:107] op_sel:[1,0]
	v_pk_mul_f32 v[104:105], v[220:221], v[104:105] op_sel:[1,0]
	v_pk_fma_f32 v[96:97], v[158:159], v[106:107], v[96:97]
	v_pk_fma_f32 v[102:103], v[134:135], s[28:29], v[102:103] op_sel_hi:[1,0,1]
	v_pk_fma_f32 v[100:101], v[132:133], s[28:29], v[100:101] op_sel_hi:[1,0,1]
	v_pk_fma_f32 v[98:99], v[156:157], v[104:105], v[98:99]
	v_pk_fma_f32 v[96:97], v[128:129], s[28:29], v[96:97] op_sel_hi:[1,0,1]
	v_pk_fma_f32 v[98:99], v[130:131], s[28:29], v[98:99] op_sel_hi:[1,0,1]
	global_store_dwordx4 v[112:113], v[100:103], off offset:512
	global_store_dwordx4 v[112:113], v[96:99], off offset:528
	v_or_b32_e32 v112, 48, v172
	v_ashrrev_i32_e32 v113, 31, v112
	v_or_b32_e32 v96, 32, v172
	v_ashrrev_i32_e32 v97, 31, v96
	v_lshl_add_u64 v[98:99], v[96:97], 3, s[16:17]
	global_load_dwordx2 v[176:177], v[98:99], off
	v_lshlrev_b64 v[178:179], 12, v[96:97]
	v_lshl_add_u64 v[96:97], s[8:9], 0, v[178:179]
	v_lshl_add_u64 v[108:109], v[96:97], 0, v[154:155]
	global_load_dwordx4 v[96:99], v[108:109], off nt
	global_load_dwordx4 v[100:103], v[108:109], off offset:16 nt
	global_load_dwordx4 v[104:107], v[108:109], off offset:512 nt
	s_nop 0
	global_load_dwordx4 v[108:111], v[108:109], off offset:528 nt
	v_lshl_add_u64 v[114:115], v[112:113], 3, s[16:17]
	global_load_dwordx2 v[180:181], v[114:115], off
	v_lshlrev_b64 v[182:183], 12, v[112:113]
	v_lshl_add_u64 v[112:113], s[8:9], 0, v[182:183]
	v_lshl_add_u64 v[124:125], v[112:113], 0, v[154:155]
	global_load_dwordx4 v[112:115], v[124:125], off nt
	global_load_dwordx4 v[116:119], v[124:125], off offset:16 nt
	global_load_dwordx4 v[120:123], v[124:125], off offset:512 nt
	s_nop 0
	global_load_dwordx4 v[124:127], v[124:125], off offset:528 nt
	s_waitcnt vmcnt(0) lgkmcnt(0)
	v_sub_f32_e32 v99, v99, v176
	v_sub_f32_e32 v98, v98, v176
	v_sub_f32_e32 v97, v97, v176
	v_sub_f32_e32 v96, v96, v176
	v_sub_f32_e32 v103, v103, v176
	v_sub_f32_e32 v102, v102, v176
	v_sub_f32_e32 v101, v101, v176
	v_pk_mul_f32 v[96:97], v[176:177], v[96:97] op_sel:[1,0]
	v_pk_mul_f32 v[98:99], v[176:177], v[98:99] op_sel:[1,0]
	v_sub_f32_e32 v100, v100, v176
	v_pk_fma_f32 v[94:95], v[168:169], v[98:99], v[94:95]
	v_pk_fma_f32 v[92:93], v[170:171], v[96:97], v[92:93]
	v_pk_mul_f32 v[96:97], v[176:177], v[100:101] op_sel:[1,0]
	v_pk_mul_f32 v[98:99], v[176:177], v[102:103] op_sel:[1,0]
	v_pk_fma_f32 v[88:89], v[166:167], v[96:97], v[88:89]
	v_pk_fma_f32 v[90:91], v[164:165], v[98:99], v[90:91]
	v_lshl_add_u64 v[96:97], s[6:7], 0, v[178:179]
	v_pk_fma_f32 v[94:95], v[142:143], s[28:29], v[94:95] op_sel_hi:[1,0,1]
	v_pk_fma_f32 v[92:93], v[140:141], s[28:29], v[92:93] op_sel_hi:[1,0,1]
	v_pk_fma_f32 v[90:91], v[138:139], s[28:29], v[90:91] op_sel_hi:[1,0,1]
	v_pk_fma_f32 v[88:89], v[136:137], s[28:29], v[88:89] op_sel_hi:[1,0,1]
	v_lshl_add_u64 v[96:97], v[96:97], 0, v[154:155]
	global_store_dwordx4 v[96:97], v[92:95], off
	global_store_dwordx4 v[96:97], v[88:91], off offset:16
	s_nop 1
	v_sub_f32_e32 v89, v107, v176
	v_sub_f32_e32 v88, v106, v176
	v_sub_f32_e32 v91, v105, v176
	v_sub_f32_e32 v90, v104, v176
	v_pk_mul_f32 v[90:91], v[176:177], v[90:91] op_sel:[1,0]
	v_pk_mul_f32 v[88:89], v[176:177], v[88:89] op_sel:[1,0]
	v_pk_fma_f32 v[84:85], v[162:163], v[90:91], v[84:85]
	v_pk_fma_f32 v[86:87], v[160:161], v[88:89], v[86:87]
	v_sub_f32_e32 v89, v111, v176
	v_sub_f32_e32 v88, v110, v176
	v_sub_f32_e32 v91, v109, v176
	v_sub_f32_e32 v90, v108, v176
	v_pk_mul_f32 v[90:91], v[176:177], v[90:91] op_sel:[1,0]
	v_pk_mul_f32 v[88:89], v[176:177], v[88:89] op_sel:[1,0]
	v_pk_fma_f32 v[76:77], v[158:159], v[90:91], v[76:77]
	v_pk_fma_f32 v[78:79], v[156:157], v[88:89], v[78:79]
	v_pk_fma_f32 v[86:87], v[134:135], s[28:29], v[86:87] op_sel_hi:[1,0,1]
	v_pk_fma_f32 v[84:85], v[132:133], s[28:29], v[84:85] op_sel_hi:[1,0,1]
	v_pk_fma_f32 v[78:79], v[130:131], s[28:29], v[78:79] op_sel_hi:[1,0,1]
	v_pk_fma_f32 v[76:77], v[128:129], s[28:29], v[76:77] op_sel_hi:[1,0,1]
	global_store_dwordx4 v[96:97], v[84:87], off offset:512
	global_store_dwordx4 v[96:97], v[76:79], off offset:528
	s_nop 1
	v_sub_f32_e32 v77, v115, v180
	v_sub_f32_e32 v76, v114, v180
	v_sub_f32_e32 v79, v113, v180
	v_sub_f32_e32 v78, v112, v180
	v_pk_mul_f32 v[78:79], v[180:181], v[78:79] op_sel:[1,0]
	v_pk_mul_f32 v[76:77], v[180:181], v[76:77] op_sel:[1,0]
	v_pk_fma_f32 v[80:81], v[170:171], v[78:79], v[80:81]
	v_pk_fma_f32 v[76:77], v[168:169], v[76:77], v[82:83]
	v_sub_f32_e32 v83, v117, v180
	v_pk_fma_f32 v[78:79], v[142:143], s[28:29], v[76:77] op_sel_hi:[1,0,1]
	v_pk_fma_f32 v[76:77], v[140:141], s[28:29], v[80:81] op_sel_hi:[1,0,1]
	v_sub_f32_e32 v81, v119, v180
	v_sub_f32_e32 v80, v118, v180
	v_sub_f32_e32 v82, v116, v180
	v_pk_mul_f32 v[80:81], v[180:181], v[80:81] op_sel:[1,0]
	v_pk_mul_f32 v[82:83], v[180:181], v[82:83] op_sel:[1,0]
	v_pk_fma_f32 v[74:75], v[164:165], v[80:81], v[74:75]
	v_lshl_add_u64 v[80:81], s[6:7], 0, v[182:183]
	v_pk_fma_f32 v[72:73], v[166:167], v[82:83], v[72:73]
	v_pk_fma_f32 v[74:75], v[138:139], s[28:29], v[74:75] op_sel_hi:[1,0,1]
	v_lshl_add_u64 v[80:81], v[80:81], 0, v[154:155]
	v_pk_fma_f32 v[72:73], v[136:137], s[28:29], v[72:73] op_sel_hi:[1,0,1]
	global_store_dwordx4 v[80:81], v[76:79], off
	global_store_dwordx4 v[80:81], v[72:75], off offset:16
	s_nop 1
	v_sub_f32_e32 v75, v121, v180
	v_sub_f32_e32 v74, v120, v180
	v_sub_f32_e32 v73, v123, v180
	v_sub_f32_e32 v72, v122, v180
	v_pk_mul_f32 v[74:75], v[180:181], v[74:75] op_sel:[1,0]
	v_pk_mul_f32 v[72:73], v[180:181], v[72:73] op_sel:[1,0]
	v_pk_fma_f32 v[68:69], v[162:163], v[74:75], v[68:69]
	v_sub_f32_e32 v75, v125, v180
	v_sub_f32_e32 v74, v124, v180
	v_pk_fma_f32 v[70:71], v[160:161], v[72:73], v[70:71]
	v_sub_f32_e32 v73, v127, v180
	v_sub_f32_e32 v72, v126, v180
	v_pk_mul_f32 v[74:75], v[180:181], v[74:75] op_sel:[1,0]
	v_pk_mul_f32 v[72:73], v[180:181], v[72:73] op_sel:[1,0]
	v_pk_fma_f32 v[64:65], v[158:159], v[74:75], v[64:65]
	v_pk_fma_f32 v[70:71], v[134:135], s[28:29], v[70:71] op_sel_hi:[1,0,1]
	v_pk_fma_f32 v[68:69], v[132:133], s[28:29], v[68:69] op_sel_hi:[1,0,1]
	v_pk_fma_f32 v[66:67], v[156:157], v[72:73], v[66:67]
	v_pk_fma_f32 v[64:65], v[128:129], s[28:29], v[64:65] op_sel_hi:[1,0,1]
	v_pk_fma_f32 v[66:67], v[130:131], s[28:29], v[66:67] op_sel_hi:[1,0,1]
	global_store_dwordx4 v[80:81], v[68:71], off offset:512
	global_store_dwordx4 v[80:81], v[64:67], off offset:528
	v_add_u32_e32 v80, 0x90, v172
	v_ashrrev_i32_e32 v81, 31, v80
	v_add_u32_e32 v64, 0x80, v172
	v_ashrrev_i32_e32 v65, 31, v64
	v_lshl_add_u64 v[66:67], v[64:65], 3, s[16:17]
	global_load_dwordx2 v[96:97], v[66:67], off
	v_lshlrev_b64 v[98:99], 12, v[64:65]
	v_lshl_add_u64 v[64:65], s[8:9], 0, v[98:99]
	v_lshl_add_u64 v[76:77], v[64:65], 0, v[154:155]
	global_load_dwordx4 v[64:67], v[76:77], off nt
	global_load_dwordx4 v[68:71], v[76:77], off offset:16 nt
	global_load_dwordx4 v[72:75], v[76:77], off offset:512 nt
	s_nop 0
	global_load_dwordx4 v[76:79], v[76:77], off offset:528 nt
	v_lshl_add_u64 v[82:83], v[80:81], 3, s[16:17]
	global_load_dwordx2 v[100:101], v[82:83], off
	v_lshlrev_b64 v[102:103], 12, v[80:81]
	v_lshl_add_u64 v[80:81], s[8:9], 0, v[102:103]
	v_lshl_add_u64 v[92:93], v[80:81], 0, v[154:155]
	global_load_dwordx4 v[80:83], v[92:93], off nt
	global_load_dwordx4 v[84:87], v[92:93], off offset:16 nt
	global_load_dwordx4 v[88:91], v[92:93], off offset:512 nt
	s_nop 0
	global_load_dwordx4 v[92:95], v[92:93], off offset:528 nt
	s_waitcnt vmcnt(0) lgkmcnt(0)
	v_sub_f32_e32 v67, v67, v96
	v_sub_f32_e32 v66, v66, v96
	v_sub_f32_e32 v65, v65, v96
	v_sub_f32_e32 v64, v64, v96
	v_pk_mul_f32 v[64:65], v[96:97], v[64:65] op_sel:[1,0]
	v_pk_mul_f32 v[66:67], v[96:97], v[66:67] op_sel:[1,0]
	v_pk_fma_f32 v[60:61], v[170:171], v[64:65], v[60:61]
	v_pk_fma_f32 v[62:63], v[168:169], v[66:67], v[62:63]
	v_sub_f32_e32 v65, v71, v96
	v_sub_f32_e32 v64, v70, v96
	v_sub_f32_e32 v67, v69, v96
	v_sub_f32_e32 v66, v68, v96
	v_pk_mul_f32 v[66:67], v[96:97], v[66:67] op_sel:[1,0]
	v_pk_mul_f32 v[64:65], v[96:97], v[64:65] op_sel:[1,0]
	v_pk_fma_f32 v[56:57], v[166:167], v[66:67], v[56:57]
	v_pk_fma_f32 v[58:59], v[164:165], v[64:65], v[58:59]
	v_lshl_add_u64 v[64:65], s[6:7], 0, v[98:99]
	v_pk_fma_f32 v[62:63], v[142:143], s[28:29], v[62:63] op_sel_hi:[1,0,1]
	v_pk_fma_f32 v[60:61], v[140:141], s[28:29], v[60:61] op_sel_hi:[1,0,1]
	v_pk_fma_f32 v[58:59], v[138:139], s[28:29], v[58:59] op_sel_hi:[1,0,1]
	v_pk_fma_f32 v[56:57], v[136:137], s[28:29], v[56:57] op_sel_hi:[1,0,1]
	v_lshl_add_u64 v[64:65], v[64:65], 0, v[154:155]
	global_store_dwordx4 v[64:65], v[60:63], off
	global_store_dwordx4 v[64:65], v[56:59], off offset:16
	s_nop 1
	v_sub_f32_e32 v57, v75, v96
	v_sub_f32_e32 v56, v74, v96
	v_sub_f32_e32 v59, v73, v96
	v_sub_f32_e32 v58, v72, v96
	v_pk_mul_f32 v[58:59], v[96:97], v[58:59] op_sel:[1,0]
	v_pk_mul_f32 v[56:57], v[96:97], v[56:57] op_sel:[1,0]
	v_pk_fma_f32 v[52:53], v[162:163], v[58:59], v[52:53]
	v_pk_fma_f32 v[54:55], v[160:161], v[56:57], v[54:55]
	v_sub_f32_e32 v57, v79, v96
	v_sub_f32_e32 v56, v78, v96
	v_sub_f32_e32 v59, v77, v96
	v_sub_f32_e32 v58, v76, v96
	v_pk_mul_f32 v[58:59], v[96:97], v[58:59] op_sel:[1,0]
	v_pk_mul_f32 v[56:57], v[96:97], v[56:57] op_sel:[1,0]
	v_pk_fma_f32 v[44:45], v[158:159], v[58:59], v[44:45]
	v_pk_fma_f32 v[46:47], v[156:157], v[56:57], v[46:47]
	v_pk_fma_f32 v[54:55], v[134:135], s[28:29], v[54:55] op_sel_hi:[1,0,1]
	v_pk_fma_f32 v[52:53], v[132:133], s[28:29], v[52:53] op_sel_hi:[1,0,1]
	v_pk_fma_f32 v[46:47], v[130:131], s[28:29], v[46:47] op_sel_hi:[1,0,1]
	v_pk_fma_f32 v[44:45], v[128:129], s[28:29], v[44:45] op_sel_hi:[1,0,1]
	global_store_dwordx4 v[64:65], v[52:55], off offset:512
	global_store_dwordx4 v[64:65], v[44:47], off offset:528
	s_nop 1
	v_sub_f32_e32 v45, v83, v100
	v_sub_f32_e32 v44, v82, v100
	v_sub_f32_e32 v47, v81, v100
	v_sub_f32_e32 v46, v80, v100
	v_pk_mul_f32 v[46:47], v[100:101], v[46:47] op_sel:[1,0]
	v_pk_mul_f32 v[44:45], v[100:101], v[44:45] op_sel:[1,0]
	v_pk_fma_f32 v[48:49], v[170:171], v[46:47], v[48:49]
	v_pk_fma_f32 v[44:45], v[168:169], v[44:45], v[50:51]
	v_sub_f32_e32 v51, v85, v100
	v_pk_fma_f32 v[46:47], v[142:143], s[28:29], v[44:45] op_sel_hi:[1,0,1]
	v_pk_fma_f32 v[44:45], v[140:141], s[28:29], v[48:49] op_sel_hi:[1,0,1]
	v_sub_f32_e32 v49, v87, v100
	v_sub_f32_e32 v48, v86, v100
	v_sub_f32_e32 v50, v84, v100
	v_pk_mul_f32 v[48:49], v[100:101], v[48:49] op_sel:[1,0]
	v_pk_mul_f32 v[50:51], v[100:101], v[50:51] op_sel:[1,0]
	v_pk_fma_f32 v[42:43], v[164:165], v[48:49], v[42:43]
	v_lshl_add_u64 v[48:49], s[6:7], 0, v[102:103]
	v_pk_fma_f32 v[40:41], v[166:167], v[50:51], v[40:41]
	v_pk_fma_f32 v[42:43], v[138:139], s[28:29], v[42:43] op_sel_hi:[1,0,1]
	v_lshl_add_u64 v[48:49], v[48:49], 0, v[154:155]
	v_pk_fma_f32 v[40:41], v[136:137], s[28:29], v[40:41] op_sel_hi:[1,0,1]
	global_store_dwordx4 v[48:49], v[44:47], off
	global_store_dwordx4 v[48:49], v[40:43], off offset:16
	s_nop 1
	v_sub_f32_e32 v43, v89, v100
	v_sub_f32_e32 v42, v88, v100
	v_sub_f32_e32 v41, v91, v100
	v_sub_f32_e32 v40, v90, v100
	v_pk_mul_f32 v[42:43], v[100:101], v[42:43] op_sel:[1,0]
	v_pk_mul_f32 v[40:41], v[100:101], v[40:41] op_sel:[1,0]
	v_pk_fma_f32 v[36:37], v[162:163], v[42:43], v[36:37]
	v_sub_f32_e32 v43, v93, v100
	v_sub_f32_e32 v42, v92, v100
	v_pk_fma_f32 v[38:39], v[160:161], v[40:41], v[38:39]
	v_sub_f32_e32 v41, v95, v100
	v_sub_f32_e32 v40, v94, v100
	v_pk_mul_f32 v[42:43], v[100:101], v[42:43] op_sel:[1,0]
	v_pk_mul_f32 v[40:41], v[100:101], v[40:41] op_sel:[1,0]
	v_pk_fma_f32 v[32:33], v[158:159], v[42:43], v[32:33]
	v_pk_fma_f32 v[38:39], v[134:135], s[28:29], v[38:39] op_sel_hi:[1,0,1]
	v_pk_fma_f32 v[36:37], v[132:133], s[28:29], v[36:37] op_sel_hi:[1,0,1]
	v_pk_fma_f32 v[34:35], v[156:157], v[40:41], v[34:35]
	v_pk_fma_f32 v[32:33], v[128:129], s[28:29], v[32:33] op_sel_hi:[1,0,1]
	v_pk_fma_f32 v[34:35], v[130:131], s[28:29], v[34:35] op_sel_hi:[1,0,1]
	global_store_dwordx4 v[48:49], v[36:39], off offset:512
	global_store_dwordx4 v[48:49], v[32:35], off offset:528
	v_add_u32_e32 v48, 0xb0, v172
	v_ashrrev_i32_e32 v49, 31, v48
	v_add_u32_e32 v32, 0xa0, v172
	v_ashrrev_i32_e32 v33, 31, v32
	v_lshl_add_u64 v[34:35], v[32:33], 3, s[16:17]
	global_load_dwordx2 v[64:65], v[34:35], off
	v_lshlrev_b64 v[66:67], 12, v[32:33]
	v_lshl_add_u64 v[32:33], s[8:9], 0, v[66:67]
	v_lshl_add_u64 v[44:45], v[32:33], 0, v[154:155]
	global_load_dwordx4 v[32:35], v[44:45], off nt
	global_load_dwordx4 v[36:39], v[44:45], off offset:16 nt
	global_load_dwordx4 v[40:43], v[44:45], off offset:512 nt
	s_nop 0
	global_load_dwordx4 v[44:47], v[44:45], off offset:528 nt
	v_lshl_add_u64 v[50:51], v[48:49], 3, s[16:17]
	global_load_dwordx2 v[68:69], v[50:51], off
	v_lshlrev_b64 v[70:71], 12, v[48:49]
	v_lshl_add_u64 v[48:49], s[8:9], 0, v[70:71]
	v_lshl_add_u64 v[60:61], v[48:49], 0, v[154:155]
	global_load_dwordx4 v[48:51], v[60:61], off nt
	global_load_dwordx4 v[52:55], v[60:61], off offset:16 nt
	global_load_dwordx4 v[56:59], v[60:61], off offset:512 nt
	s_nop 0
	global_load_dwordx4 v[60:63], v[60:61], off offset:528 nt
	s_waitcnt vmcnt(0) lgkmcnt(0)
	v_sub_f32_e32 v35, v35, v64
	v_sub_f32_e32 v34, v34, v64
	v_sub_f32_e32 v33, v33, v64
	v_sub_f32_e32 v32, v32, v64
	v_pk_mul_f32 v[32:33], v[64:65], v[32:33] op_sel:[1,0]
	v_pk_mul_f32 v[34:35], v[64:65], v[34:35] op_sel:[1,0]
	v_pk_fma_f32 v[28:29], v[170:171], v[32:33], v[28:29]
	v_pk_fma_f32 v[30:31], v[168:169], v[34:35], v[30:31]
	v_sub_f32_e32 v33, v39, v64
	v_sub_f32_e32 v32, v38, v64
	v_sub_f32_e32 v35, v37, v64
	v_sub_f32_e32 v34, v36, v64
	v_pk_mul_f32 v[34:35], v[64:65], v[34:35] op_sel:[1,0]
	v_pk_mul_f32 v[32:33], v[64:65], v[32:33] op_sel:[1,0]
	v_pk_fma_f32 v[24:25], v[166:167], v[34:35], v[24:25]
	v_pk_fma_f32 v[26:27], v[164:165], v[32:33], v[26:27]
	v_lshl_add_u64 v[32:33], s[6:7], 0, v[66:67]
	v_pk_fma_f32 v[30:31], v[142:143], s[28:29], v[30:31] op_sel_hi:[1,0,1]
	v_pk_fma_f32 v[28:29], v[140:141], s[28:29], v[28:29] op_sel_hi:[1,0,1]
	v_pk_fma_f32 v[26:27], v[138:139], s[28:29], v[26:27] op_sel_hi:[1,0,1]
	v_pk_fma_f32 v[24:25], v[136:137], s[28:29], v[24:25] op_sel_hi:[1,0,1]
	v_lshl_add_u64 v[32:33], v[32:33], 0, v[154:155]
	global_store_dwordx4 v[32:33], v[28:31], off
	global_store_dwordx4 v[32:33], v[24:27], off offset:16
	s_nop 1
	v_sub_f32_e32 v25, v43, v64
	v_sub_f32_e32 v24, v42, v64
	v_sub_f32_e32 v27, v41, v64
	v_sub_f32_e32 v26, v40, v64
	v_pk_mul_f32 v[26:27], v[64:65], v[26:27] op_sel:[1,0]
	v_pk_mul_f32 v[24:25], v[64:65], v[24:25] op_sel:[1,0]
	v_pk_fma_f32 v[20:21], v[162:163], v[26:27], v[20:21]
	v_pk_fma_f32 v[22:23], v[160:161], v[24:25], v[22:23]
	v_sub_f32_e32 v25, v47, v64
	v_sub_f32_e32 v24, v46, v64
	v_sub_f32_e32 v27, v45, v64
	v_sub_f32_e32 v26, v44, v64
	v_pk_mul_f32 v[26:27], v[64:65], v[26:27] op_sel:[1,0]
	v_pk_mul_f32 v[24:25], v[64:65], v[24:25] op_sel:[1,0]
	v_pk_fma_f32 v[12:13], v[158:159], v[26:27], v[12:13]
	v_pk_fma_f32 v[14:15], v[156:157], v[24:25], v[14:15]
	v_pk_fma_f32 v[22:23], v[134:135], s[28:29], v[22:23] op_sel_hi:[1,0,1]
	v_pk_fma_f32 v[20:21], v[132:133], s[28:29], v[20:21] op_sel_hi:[1,0,1]
	v_pk_fma_f32 v[14:15], v[130:131], s[28:29], v[14:15] op_sel_hi:[1,0,1]
	v_pk_fma_f32 v[12:13], v[128:129], s[28:29], v[12:13] op_sel_hi:[1,0,1]
	global_store_dwordx4 v[32:33], v[20:23], off offset:512
	global_store_dwordx4 v[32:33], v[12:15], off offset:528
	s_nop 1
	v_sub_f32_e32 v13, v51, v68
	v_sub_f32_e32 v12, v50, v68
	v_sub_f32_e32 v15, v49, v68
	v_sub_f32_e32 v14, v48, v68
	v_pk_mul_f32 v[14:15], v[68:69], v[14:15] op_sel:[1,0]
	v_pk_mul_f32 v[12:13], v[68:69], v[12:13] op_sel:[1,0]
	v_pk_fma_f32 v[16:17], v[170:171], v[14:15], v[16:17]
	v_pk_fma_f32 v[12:13], v[168:169], v[12:13], v[18:19]
	v_sub_f32_e32 v19, v53, v68
	v_pk_fma_f32 v[14:15], v[142:143], s[28:29], v[12:13] op_sel_hi:[1,0,1]
	v_pk_fma_f32 v[12:13], v[140:141], s[28:29], v[16:17] op_sel_hi:[1,0,1]
	v_sub_f32_e32 v17, v55, v68
	v_sub_f32_e32 v16, v54, v68
	v_sub_f32_e32 v18, v52, v68
	v_pk_mul_f32 v[18:19], v[68:69], v[18:19] op_sel:[1,0]
	v_pk_mul_f32 v[16:17], v[68:69], v[16:17] op_sel:[1,0]
	v_pk_fma_f32 v[8:9], v[166:167], v[18:19], v[8:9]
	v_pk_fma_f32 v[10:11], v[164:165], v[16:17], v[10:11]
	v_lshl_add_u64 v[16:17], s[6:7], 0, v[70:71]
	v_pk_fma_f32 v[10:11], v[138:139], s[28:29], v[10:11] op_sel_hi:[1,0,1]
	v_pk_fma_f32 v[8:9], v[136:137], s[28:29], v[8:9] op_sel_hi:[1,0,1]
	v_lshl_add_u64 v[16:17], v[16:17], 0, v[154:155]
	global_store_dwordx4 v[16:17], v[12:15], off
	global_store_dwordx4 v[16:17], v[8:11], off offset:16
	s_nop 1
	v_sub_f32_e32 v9, v59, v68
	v_sub_f32_e32 v8, v58, v68
	v_sub_f32_e32 v11, v57, v68
	v_sub_f32_e32 v10, v56, v68
	v_pk_mul_f32 v[10:11], v[68:69], v[10:11] op_sel:[1,0]
	v_pk_mul_f32 v[8:9], v[68:69], v[8:9] op_sel:[1,0]
	v_pk_fma_f32 v[4:5], v[162:163], v[10:11], v[4:5]
	v_pk_fma_f32 v[6:7], v[160:161], v[8:9], v[6:7]
	v_sub_f32_e32 v9, v63, v68
	v_sub_f32_e32 v8, v62, v68
	v_sub_f32_e32 v11, v61, v68
	v_sub_f32_e32 v10, v60, v68
	v_pk_mul_f32 v[10:11], v[68:69], v[10:11] op_sel:[1,0]
	v_pk_mul_f32 v[8:9], v[68:69], v[8:9] op_sel:[1,0]
	v_pk_fma_f32 v[6:7], v[134:135], s[28:29], v[6:7] op_sel_hi:[1,0,1]
	v_pk_fma_f32 v[4:5], v[132:133], s[28:29], v[4:5] op_sel_hi:[1,0,1]
	v_pk_fma_f32 v[2:3], v[156:157], v[8:9], v[2:3]
	v_pk_fma_f32 v[0:1], v[158:159], v[10:11], v[0:1]
	v_pk_fma_f32 v[2:3], v[130:131], s[28:29], v[2:3] op_sel_hi:[1,0,1]
	v_pk_fma_f32 v[0:1], v[128:129], s[28:29], v[0:1] op_sel_hi:[1,0,1]
	global_store_dwordx4 v[16:17], v[4:7], off offset:512
	global_store_dwordx4 v[16:17], v[0:3], off offset:528
	s_cbranch_vccnz .LBB0_1156
	s_andn2_b64 vcc, exec, s[14:15]
	s_cbranch_vccnz .LBB0_1155
	s_barrier
	s_branch .LBB0_1155

.LBB0_1495:
	v_mbcnt_lo_u32_b32 v148, -1, 0
	v_mbcnt_hi_u32_b32 v148, -1, v148
	s_lshl_b32 s21, s29, 8
	v_ashrrev_i32_e32 v88, 1, v148
	v_and_b32_e32 v88, -8, v88
	s_or_b32 s21, s21, s51
	v_add_u32_e32 v144, s21, v88
	v_ashrrev_i32_e32 v145, 31, v144
	v_lshlrev_b64 v[206:207], 2, v[144:145]
	v_lshl_add_u64 v[92:93], s[14:15], 0, v[206:207]
	global_load_dwordx4 v[88:91], v[92:93], off nt
	s_mov_b32 s30, 0x3fb504f3
	v_lshl_add_u64 v[146:147], s[16:17], 0, v[206:207]
	s_lshl_b32 s21, s28, 8
	s_add_i32 s21, s21, s50
	v_and_or_b32 v208, v148, 15, s21
	v_ashrrev_i32_e32 v209, 31, v208
	v_lshlrev_b64 v[148:149], 11, v[208:209]
	v_lshl_add_u64 v[148:149], s[10:11], 0, v[148:149]
	v_lshlrev_b64 v[210:211], 1, v[144:145]
	v_lshl_add_u64 v[144:145], v[148:149], 0, v[210:211]
	s_mov_b64 s[28:29], -1
	s_andn2_b64 vcc, exec, s[4:5]
	s_waitcnt vmcnt(0) lgkmcnt(0)
	v_pk_mul_f32 v[202:203], v[90:91], s[30:31] op_sel_hi:[1,0]
	v_pk_mul_f32 v[204:205], v[88:89], s[30:31] op_sel_hi:[1,0]
	global_load_dwordx4 v[88:91], v[92:93], off offset:16 nt
	s_waitcnt vmcnt(0) lgkmcnt(0)
	v_pk_mul_f32 v[198:199], v[90:91], s[30:31] op_sel_hi:[1,0]
	v_pk_mul_f32 v[200:201], v[88:89], s[30:31] op_sel_hi:[1,0]
	global_load_dwordx4 v[100:103], v[146:147], off nt
	global_load_dwordx4 v[96:99], v[146:147], off offset:16 nt
	global_load_dwordx4 v[88:91], v[92:93], off offset:512 nt
	s_waitcnt vmcnt(0) lgkmcnt(0)
	v_pk_mul_f32 v[194:195], v[90:91], s[30:31] op_sel_hi:[1,0]
	v_pk_mul_f32 v[196:197], v[88:89], s[30:31] op_sel_hi:[1,0]
	global_load_dwordx4 v[88:91], v[92:93], off offset:528 nt
	s_waitcnt vmcnt(0) lgkmcnt(0)
	v_pk_mul_f32 v[190:191], v[90:91], s[30:31] op_sel_hi:[1,0]
	v_pk_mul_f32 v[192:193], v[88:89], s[30:31] op_sel_hi:[1,0]
	global_load_dwordx4 v[92:95], v[146:147], off offset:512 nt
	global_load_dwordx4 v[88:91], v[146:147], off offset:528 nt
	v_lshl_add_u64 v[146:147], v[208:209], 3, s[12:13]
	global_load_dwordx2 v[218:219], v[146:147], off
	v_lshlrev_b64 v[146:147], 12, v[208:209]
	v_lshl_add_u64 v[146:147], s[6:7], 0, v[146:147]
	v_lshl_add_u64 v[216:217], v[146:147], 0, v[206:207]
	global_load_dwordx4 v[222:225], v[216:217], off nt
	global_load_dwordx4 v[226:229], v[216:217], off offset:16 nt
	global_load_dwordx4 v[234:237], v[144:145], off nt
	global_load_dwordx4 v[176:179], v[216:217], off offset:512 nt
	global_load_dwordx4 v[172:175], v[216:217], off offset:528 nt
	global_load_dwordx4 v[164:167], v[144:145], off offset:256 nt
	v_or_b32_e32 v144, 16, v208
	v_ashrrev_i32_e32 v145, 31, v144
	v_lshl_add_u64 v[146:147], v[144:145], 3, s[12:13]
	global_load_dwordx2 v[214:215], v[146:147], off
	v_lshlrev_b64 v[146:147], 12, v[144:145]
	v_lshl_add_u64 v[146:147], s[6:7], 0, v[146:147]
	v_lshl_add_u64 v[212:213], v[146:147], 0, v[206:207]
	global_load_dwordx4 v[168:171], v[212:213], off nt
	global_load_dwordx4 v[160:163], v[212:213], off offset:16 nt
	v_lshlrev_b64 v[144:145], 11, v[144:145]
	v_lshl_add_u64 v[144:145], s[10:11], 0, v[144:145]
	v_lshl_add_u64 v[144:145], v[144:145], 0, v[210:211]
	global_load_dwordx4 v[156:159], v[144:145], off nt
	global_load_dwordx4 v[152:155], v[212:213], off offset:512 nt
	global_load_dwordx4 v[148:151], v[212:213], off offset:528 nt
	s_nop 0
	global_load_dwordx4 v[144:147], v[144:145], off offset:256 nt
	s_waitcnt vmcnt(0) lgkmcnt(0)
	v_sub_f32_e32 v225, v225, v218
	v_sub_f32_e32 v224, v224, v218
	v_sub_f32_e32 v223, v223, v218
	v_sub_f32_e32 v222, v222, v218
	v_pk_mul_f32 v[222:223], v[218:219], v[222:223] op_sel:[1,0]
	v_pk_mul_f32 v[224:225], v[218:219], v[224:225] op_sel:[1,0]
	v_pk_fma_f32 v[140:141], v[204:205], v[222:223], v[140:141]
	v_pk_fma_f32 v[142:143], v[202:203], v[224:225], v[142:143]
	v_sub_f32_e32 v223, v229, v218
	v_sub_f32_e32 v222, v228, v218
	v_sub_f32_e32 v225, v227, v218
	v_sub_f32_e32 v224, v226, v218
	v_pk_mul_f32 v[224:225], v[218:219], v[224:225] op_sel:[1,0]
	v_pk_mul_f32 v[222:223], v[218:219], v[222:223] op_sel:[1,0]
	v_pk_fma_f32 v[136:137], v[200:201], v[224:225], v[136:137]
	v_pk_fma_f32 v[138:139], v[198:199], v[222:223], v[138:139]
	v_pk_fma_f32 v[142:143], v[102:103], s[30:31], v[142:143] op_sel_hi:[1,0,1]
	v_pk_fma_f32 v[140:141], v[100:101], s[30:31], v[140:141] op_sel_hi:[1,0,1]
	v_pk_fma_f32 v[222:223], v[98:99], s[30:31], v[138:139] op_sel_hi:[1,0,1]
	v_pk_fma_f32 v[224:225], v[96:97], s[30:31], v[136:137] op_sel_hi:[1,0,1]
	v_lshlrev_b32_e32 v136, 16, v234
	v_and_b32_e32 v137, 0xffff0000, v234
	v_lshlrev_b32_e32 v138, 16, v235
	v_and_b32_e32 v139, 0xffff0000, v235
	v_pk_add_f32 v[136:137], v[140:141], v[136:137]
	v_pk_add_f32 v[138:139], v[142:143], v[138:139]
	v_lshlrev_b32_e32 v140, 16, v236
	v_and_b32_e32 v141, 0xffff0000, v236
	v_lshlrev_b32_e32 v142, 16, v237
	v_and_b32_e32 v143, 0xffff0000, v237
	v_pk_add_f32 v[140:141], v[224:225], v[140:141]
	v_pk_add_f32 v[142:143], v[222:223], v[142:143]
	global_store_dwordx4 v[216:217], v[136:139], off
	global_store_dwordx4 v[216:217], v[140:143], off offset:16
	s_nop 0
	v_sub_f32_e32 v137, v179, v218
	v_sub_f32_e32 v136, v178, v218
	v_sub_f32_e32 v139, v177, v218
	v_sub_f32_e32 v138, v176, v218
	v_pk_mul_f32 v[138:139], v[218:219], v[138:139] op_sel:[1,0]
	v_pk_mul_f32 v[136:137], v[218:219], v[136:137] op_sel:[1,0]
	v_pk_fma_f32 v[132:133], v[196:197], v[138:139], v[132:133]
	v_pk_fma_f32 v[134:135], v[194:195], v[136:137], v[134:135]
	v_sub_f32_e32 v137, v175, v218
	v_sub_f32_e32 v136, v174, v218
	v_sub_f32_e32 v139, v173, v218
	v_sub_f32_e32 v138, v172, v218
	v_pk_mul_f32 v[138:139], v[218:219], v[138:139] op_sel:[1,0]
	v_pk_mul_f32 v[136:137], v[218:219], v[136:137] op_sel:[1,0]
	v_pk_fma_f32 v[128:129], v[192:193], v[138:139], v[128:129]
	v_pk_fma_f32 v[130:131], v[190:191], v[136:137], v[130:131]
	v_pk_fma_f32 v[134:135], v[94:95], s[30:31], v[134:135] op_sel_hi:[1,0,1]
	v_pk_fma_f32 v[132:133], v[92:93], s[30:31], v[132:133] op_sel_hi:[1,0,1]
	v_pk_fma_f32 v[136:137], v[90:91], s[30:31], v[130:131] op_sel_hi:[1,0,1]
	v_pk_fma_f32 v[138:139], v[88:89], s[30:31], v[128:129] op_sel_hi:[1,0,1]
	v_lshlrev_b32_e32 v128, 16, v164
	v_and_b32_e32 v129, 0xffff0000, v164
	v_lshlrev_b32_e32 v130, 16, v165
	v_and_b32_e32 v131, 0xffff0000, v165
	v_pk_add_f32 v[128:129], v[132:133], v[128:129]
	v_pk_add_f32 v[130:131], v[134:135], v[130:131]
	v_lshlrev_b32_e32 v132, 16, v166
	v_and_b32_e32 v133, 0xffff0000, v166
	v_lshlrev_b32_e32 v134, 16, v167
	v_and_b32_e32 v135, 0xffff0000, v167
	v_pk_add_f32 v[132:133], v[138:139], v[132:133]
	v_pk_add_f32 v[134:135], v[136:137], v[134:135]
	global_store_dwordx4 v[216:217], v[128:131], off offset:512
	global_store_dwordx4 v[216:217], v[132:135], off offset:528
	s_nop 0
	v_sub_f32_e32 v129, v171, v214
	v_sub_f32_e32 v128, v170, v214
	v_sub_f32_e32 v131, v169, v214
	v_sub_f32_e32 v130, v168, v214
	v_pk_mul_f32 v[130:131], v[214:215], v[130:131] op_sel:[1,0]
	v_pk_mul_f32 v[128:129], v[214:215], v[128:129] op_sel:[1,0]
	v_pk_fma_f32 v[124:125], v[204:205], v[130:131], v[124:125]
	v_pk_fma_f32 v[126:127], v[202:203], v[128:129], v[126:127]
	v_sub_f32_e32 v129, v163, v214
	v_sub_f32_e32 v128, v162, v214
	v_sub_f32_e32 v131, v161, v214
	v_sub_f32_e32 v130, v160, v214
	v_pk_mul_f32 v[130:131], v[214:215], v[130:131] op_sel:[1,0]
	v_pk_mul_f32 v[128:129], v[214:215], v[128:129] op_sel:[1,0]
	v_pk_fma_f32 v[120:121], v[200:201], v[130:131], v[120:121]
	v_pk_fma_f32 v[122:123], v[198:199], v[128:129], v[122:123]
	v_pk_fma_f32 v[126:127], v[102:103], s[30:31], v[126:127] op_sel_hi:[1,0,1]
	v_pk_fma_f32 v[124:125], v[100:101], s[30:31], v[124:125] op_sel_hi:[1,0,1]
	v_pk_fma_f32 v[128:129], v[98:99], s[30:31], v[122:123] op_sel_hi:[1,0,1]
	v_pk_fma_f32 v[130:131], v[96:97], s[30:31], v[120:121] op_sel_hi:[1,0,1]
	v_lshlrev_b32_e32 v120, 16, v156
	v_and_b32_e32 v121, 0xffff0000, v156
	v_lshlrev_b32_e32 v122, 16, v157
	v_and_b32_e32 v123, 0xffff0000, v157
	v_pk_add_f32 v[120:121], v[124:125], v[120:121]
	v_pk_add_f32 v[122:123], v[126:127], v[122:123]
	v_lshlrev_b32_e32 v124, 16, v158
	v_and_b32_e32 v125, 0xffff0000, v158
	v_lshlrev_b32_e32 v126, 16, v159
	v_and_b32_e32 v127, 0xffff0000, v159
	v_pk_add_f32 v[124:125], v[130:131], v[124:125]
	v_pk_add_f32 v[126:127], v[128:129], v[126:127]
	global_store_dwordx4 v[212:213], v[120:123], off
	global_store_dwordx4 v[212:213], v[124:127], off offset:16
	s_nop 0
	v_sub_f32_e32 v121, v155, v214
	v_sub_f32_e32 v120, v154, v214
	v_sub_f32_e32 v123, v153, v214
	v_sub_f32_e32 v122, v152, v214
	v_pk_mul_f32 v[122:123], v[214:215], v[122:123] op_sel:[1,0]
	v_pk_mul_f32 v[120:121], v[214:215], v[120:121] op_sel:[1,0]
	v_pk_fma_f32 v[116:117], v[196:197], v[122:123], v[116:117]
	v_pk_fma_f32 v[118:119], v[194:195], v[120:121], v[118:119]
	v_sub_f32_e32 v121, v151, v214
	v_sub_f32_e32 v120, v150, v214
	v_sub_f32_e32 v123, v149, v214
	v_sub_f32_e32 v122, v148, v214
	v_pk_mul_f32 v[122:123], v[214:215], v[122:123] op_sel:[1,0]
	v_pk_mul_f32 v[120:121], v[214:215], v[120:121] op_sel:[1,0]
	v_pk_fma_f32 v[112:113], v[192:193], v[122:123], v[112:113]
	v_pk_fma_f32 v[114:115], v[190:191], v[120:121], v[114:115]
	v_pk_fma_f32 v[118:119], v[94:95], s[30:31], v[118:119] op_sel_hi:[1,0,1]
	v_pk_fma_f32 v[116:117], v[92:93], s[30:31], v[116:117] op_sel_hi:[1,0,1]
	v_pk_fma_f32 v[120:121], v[90:91], s[30:31], v[114:115] op_sel_hi:[1,0,1]
	v_pk_fma_f32 v[122:123], v[88:89], s[30:31], v[112:113] op_sel_hi:[1,0,1]
	v_lshlrev_b32_e32 v112, 16, v144
	v_and_b32_e32 v113, 0xffff0000, v144
	v_lshlrev_b32_e32 v114, 16, v145
	v_and_b32_e32 v115, 0xffff0000, v145
	v_pk_add_f32 v[112:113], v[116:117], v[112:113]
	v_pk_add_f32 v[114:115], v[118:119], v[114:115]
	v_lshlrev_b32_e32 v116, 16, v146
	v_and_b32_e32 v117, 0xffff0000, v146
	v_lshlrev_b32_e32 v118, 16, v147
	v_and_b32_e32 v119, 0xffff0000, v147
	v_pk_add_f32 v[116:117], v[122:123], v[116:117]
	v_pk_add_f32 v[118:119], v[120:121], v[118:119]
	global_store_dwordx4 v[212:213], v[112:115], off offset:512
	global_store_dwordx4 v[212:213], v[116:119], off offset:528
	s_nop 0
	v_or_b32_e32 v112, 32, v208
	v_ashrrev_i32_e32 v113, 31, v112
	v_lshl_add_u64 v[114:115], v[112:113], 3, s[12:13]
	global_load_dwordx2 v[162:163], v[114:115], off
	v_lshlrev_b64 v[114:115], 12, v[112:113]
	v_lshl_add_u64 v[114:115], s[6:7], 0, v[114:115]
	v_lshl_add_u64 v[164:165], v[114:115], 0, v[206:207]
	global_load_dwordx4 v[114:117], v[164:165], off nt
	global_load_dwordx4 v[118:121], v[164:165], off offset:16 nt
	v_lshlrev_b64 v[112:113], 11, v[112:113]
	v_lshl_add_u64 v[112:113], s[10:11], 0, v[112:113]
	v_lshl_add_u64 v[112:113], v[112:113], 0, v[210:211]
	global_load_dwordx4 v[122:125], v[112:113], off nt
	global_load_dwordx4 v[126:129], v[164:165], off offset:512 nt
	global_load_dwordx4 v[130:133], v[164:165], off offset:528 nt
	global_load_dwordx4 v[134:137], v[112:113], off offset:256 nt
	v_or_b32_e32 v112, 48, v208
	v_ashrrev_i32_e32 v113, 31, v112
	v_lshl_add_u64 v[138:139], v[112:113], 3, s[12:13]
	global_load_dwordx2 v[166:167], v[138:139], off
	v_lshlrev_b64 v[138:139], 12, v[112:113]
	v_lshl_add_u64 v[138:139], s[6:7], 0, v[138:139]
	v_lshlrev_b64 v[112:113], 11, v[112:113]
	v_lshl_add_u64 v[146:147], s[10:11], 0, v[112:113]
	v_lshl_add_u64 v[112:113], v[138:139], 0, v[206:207]
	global_load_dwordx4 v[138:141], v[112:113], off nt
	global_load_dwordx4 v[142:145], v[112:113], off offset:16 nt
	v_lshl_add_u64 v[158:159], v[146:147], 0, v[210:211]
	global_load_dwordx4 v[146:149], v[158:159], off nt
	global_load_dwordx4 v[150:153], v[112:113], off offset:512 nt
	global_load_dwordx4 v[154:157], v[112:113], off offset:528 nt
	s_nop 0
	global_load_dwordx4 v[158:161], v[158:159], off offset:256 nt
	s_waitcnt vmcnt(0) lgkmcnt(0)
	v_sub_f32_e32 v117, v117, v162
	v_sub_f32_e32 v116, v116, v162
	v_sub_f32_e32 v115, v115, v162
	v_sub_f32_e32 v114, v114, v162
	v_pk_mul_f32 v[114:115], v[162:163], v[114:115] op_sel:[1,0]
	v_pk_mul_f32 v[116:117], v[162:163], v[116:117] op_sel:[1,0]
	v_pk_fma_f32 v[108:109], v[204:205], v[114:115], v[108:109]
	v_pk_fma_f32 v[110:111], v[202:203], v[116:117], v[110:111]
	v_sub_f32_e32 v115, v121, v162
	v_sub_f32_e32 v114, v120, v162
	v_sub_f32_e32 v117, v119, v162
	v_sub_f32_e32 v116, v118, v162
	v_pk_mul_f32 v[116:117], v[162:163], v[116:117] op_sel:[1,0]
	v_pk_mul_f32 v[114:115], v[162:163], v[114:115] op_sel:[1,0]
	v_pk_fma_f32 v[104:105], v[200:201], v[116:117], v[104:105]
	v_pk_fma_f32 v[106:107], v[198:199], v[114:115], v[106:107]
	v_pk_fma_f32 v[110:111], v[102:103], s[30:31], v[110:111] op_sel_hi:[1,0,1]
	v_pk_fma_f32 v[108:109], v[100:101], s[30:31], v[108:109] op_sel_hi:[1,0,1]
	v_pk_fma_f32 v[114:115], v[98:99], s[30:31], v[106:107] op_sel_hi:[1,0,1]
	v_pk_fma_f32 v[116:117], v[96:97], s[30:31], v[104:105] op_sel_hi:[1,0,1]
	v_lshlrev_b32_e32 v104, 16, v122
	v_and_b32_e32 v105, 0xffff0000, v122
	v_lshlrev_b32_e32 v106, 16, v123
	v_and_b32_e32 v107, 0xffff0000, v123
	v_pk_add_f32 v[104:105], v[108:109], v[104:105]
	v_pk_add_f32 v[106:107], v[110:111], v[106:107]
	v_lshlrev_b32_e32 v108, 16, v124
	v_and_b32_e32 v109, 0xffff0000, v124
	v_lshlrev_b32_e32 v110, 16, v125
	v_and_b32_e32 v111, 0xffff0000, v125
	v_pk_add_f32 v[108:109], v[116:117], v[108:109]
	v_pk_add_f32 v[110:111], v[114:115], v[110:111]
	global_store_dwordx4 v[164:165], v[104:107], off
	global_store_dwordx4 v[164:165], v[108:111], off offset:16
	s_nop 0
	v_sub_f32_e32 v105, v129, v162
	v_sub_f32_e32 v104, v128, v162
	v_sub_f32_e32 v107, v127, v162
	v_sub_f32_e32 v106, v126, v162
	v_pk_mul_f32 v[106:107], v[162:163], v[106:107] op_sel:[1,0]
	v_pk_mul_f32 v[104:105], v[162:163], v[104:105] op_sel:[1,0]
	v_pk_fma_f32 v[84:85], v[196:197], v[106:107], v[84:85]
	v_pk_fma_f32 v[86:87], v[194:195], v[104:105], v[86:87]
	v_sub_f32_e32 v105, v133, v162
	v_sub_f32_e32 v104, v132, v162
	v_sub_f32_e32 v107, v131, v162
	v_sub_f32_e32 v106, v130, v162
	v_pk_mul_f32 v[106:107], v[162:163], v[106:107] op_sel:[1,0]
	v_pk_mul_f32 v[104:105], v[162:163], v[104:105] op_sel:[1,0]
	v_pk_fma_f32 v[80:81], v[192:193], v[106:107], v[80:81]
	v_pk_fma_f32 v[82:83], v[190:191], v[104:105], v[82:83]
	v_pk_fma_f32 v[86:87], v[94:95], s[30:31], v[86:87] op_sel_hi:[1,0,1]
	v_pk_fma_f32 v[84:85], v[92:93], s[30:31], v[84:85] op_sel_hi:[1,0,1]
	v_pk_fma_f32 v[104:105], v[90:91], s[30:31], v[82:83] op_sel_hi:[1,0,1]
	v_pk_fma_f32 v[106:107], v[88:89], s[30:31], v[80:81] op_sel_hi:[1,0,1]
	v_lshlrev_b32_e32 v80, 16, v134
	v_and_b32_e32 v81, 0xffff0000, v134
	v_lshlrev_b32_e32 v82, 16, v135
	v_and_b32_e32 v83, 0xffff0000, v135
	v_pk_add_f32 v[80:81], v[84:85], v[80:81]
	v_pk_add_f32 v[82:83], v[86:87], v[82:83]
	v_lshlrev_b32_e32 v84, 16, v136
	v_and_b32_e32 v85, 0xffff0000, v136
	v_lshlrev_b32_e32 v86, 16, v137
	v_and_b32_e32 v87, 0xffff0000, v137
	v_pk_add_f32 v[84:85], v[106:107], v[84:85]
	v_pk_add_f32 v[86:87], v[104:105], v[86:87]
	global_store_dwordx4 v[164:165], v[80:83], off offset:512
	global_store_dwordx4 v[164:165], v[84:87], off offset:528
	s_nop 0
	v_sub_f32_e32 v81, v141, v166
	v_sub_f32_e32 v80, v140, v166
	v_sub_f32_e32 v83, v139, v166
	v_sub_f32_e32 v82, v138, v166
	v_pk_mul_f32 v[82:83], v[166:167], v[82:83] op_sel:[1,0]
	v_pk_mul_f32 v[80:81], v[166:167], v[80:81] op_sel:[1,0]
	v_pk_fma_f32 v[76:77], v[204:205], v[82:83], v[76:77]
	v_pk_fma_f32 v[78:79], v[202:203], v[80:81], v[78:79]
	v_sub_f32_e32 v81, v145, v166
	v_sub_f32_e32 v80, v144, v166
	v_sub_f32_e32 v83, v143, v166
	v_sub_f32_e32 v82, v142, v166
	v_pk_mul_f32 v[82:83], v[166:167], v[82:83] op_sel:[1,0]
	v_pk_mul_f32 v[80:81], v[166:167], v[80:81] op_sel:[1,0]
	v_pk_fma_f32 v[72:73], v[200:201], v[82:83], v[72:73]
	v_pk_fma_f32 v[74:75], v[198:199], v[80:81], v[74:75]
	v_pk_fma_f32 v[78:79], v[102:103], s[30:31], v[78:79] op_sel_hi:[1,0,1]
	v_pk_fma_f32 v[76:77], v[100:101], s[30:31], v[76:77] op_sel_hi:[1,0,1]
	v_pk_fma_f32 v[80:81], v[98:99], s[30:31], v[74:75] op_sel_hi:[1,0,1]
	v_pk_fma_f32 v[82:83], v[96:97], s[30:31], v[72:73] op_sel_hi:[1,0,1]
	v_lshlrev_b32_e32 v72, 16, v146
	v_and_b32_e32 v73, 0xffff0000, v146
	v_lshlrev_b32_e32 v74, 16, v147
	v_and_b32_e32 v75, 0xffff0000, v147
	v_pk_add_f32 v[72:73], v[76:77], v[72:73]
	v_pk_add_f32 v[74:75], v[78:79], v[74:75]
	v_lshlrev_b32_e32 v76, 16, v148
	v_and_b32_e32 v77, 0xffff0000, v148
	v_lshlrev_b32_e32 v78, 16, v149
	v_and_b32_e32 v79, 0xffff0000, v149
	v_pk_add_f32 v[76:77], v[82:83], v[76:77]
	v_pk_add_f32 v[78:79], v[80:81], v[78:79]
	global_store_dwordx4 v[112:113], v[72:75], off
	global_store_dwordx4 v[112:113], v[76:79], off offset:16
	s_nop 0
	v_sub_f32_e32 v73, v153, v166
	v_sub_f32_e32 v72, v152, v166
	v_sub_f32_e32 v75, v151, v166
	v_sub_f32_e32 v74, v150, v166
	v_pk_mul_f32 v[74:75], v[166:167], v[74:75] op_sel:[1,0]
	v_pk_mul_f32 v[72:73], v[166:167], v[72:73] op_sel:[1,0]
	v_pk_fma_f32 v[68:69], v[196:197], v[74:75], v[68:69]
	v_pk_fma_f32 v[70:71], v[194:195], v[72:73], v[70:71]
	v_sub_f32_e32 v73, v157, v166
	v_sub_f32_e32 v72, v156, v166
	v_sub_f32_e32 v75, v155, v166
	v_sub_f32_e32 v74, v154, v166
	v_pk_mul_f32 v[74:75], v[166:167], v[74:75] op_sel:[1,0]
	v_pk_mul_f32 v[72:73], v[166:167], v[72:73] op_sel:[1,0]
	v_pk_fma_f32 v[64:65], v[192:193], v[74:75], v[64:65]
	v_pk_fma_f32 v[66:67], v[190:191], v[72:73], v[66:67]
	v_pk_fma_f32 v[70:71], v[94:95], s[30:31], v[70:71] op_sel_hi:[1,0,1]
	v_pk_fma_f32 v[68:69], v[92:93], s[30:31], v[68:69] op_sel_hi:[1,0,1]
	v_pk_fma_f32 v[72:73], v[90:91], s[30:31], v[66:67] op_sel_hi:[1,0,1]
	v_pk_fma_f32 v[74:75], v[88:89], s[30:31], v[64:65] op_sel_hi:[1,0,1]
	v_lshlrev_b32_e32 v64, 16, v158
	v_and_b32_e32 v65, 0xffff0000, v158
	v_lshlrev_b32_e32 v66, 16, v159
	v_and_b32_e32 v67, 0xffff0000, v159
	v_pk_add_f32 v[64:65], v[68:69], v[64:65]
	v_pk_add_f32 v[66:67], v[70:71], v[66:67]
	v_lshlrev_b32_e32 v68, 16, v160
	v_and_b32_e32 v69, 0xffff0000, v160
	v_lshlrev_b32_e32 v70, 16, v161
	v_and_b32_e32 v71, 0xffff0000, v161
	v_pk_add_f32 v[68:69], v[74:75], v[68:69]
	v_pk_add_f32 v[70:71], v[72:73], v[70:71]
	global_store_dwordx4 v[112:113], v[64:67], off offset:512
	global_store_dwordx4 v[112:113], v[68:71], off offset:528
	s_nop 0
	v_add_u32_e32 v64, 0x80, v208
	v_ashrrev_i32_e32 v65, 31, v64
	v_lshl_add_u64 v[66:67], v[64:65], 3, s[12:13]
	global_load_dwordx2 v[86:87], v[66:67], off
	v_lshlrev_b64 v[66:67], 12, v[64:65]
	v_lshl_add_u64 v[66:67], s[6:7], 0, v[66:67]
	v_lshl_add_u64 v[132:133], v[66:67], 0, v[206:207]
	global_load_dwordx4 v[66:69], v[132:133], off nt
	global_load_dwordx4 v[70:73], v[132:133], off offset:16 nt
	v_lshlrev_b64 v[64:65], 11, v[64:65]
	v_lshl_add_u64 v[64:65], s[10:11], 0, v[64:65]
	v_lshl_add_u64 v[64:65], v[64:65], 0, v[210:211]
	global_load_dwordx4 v[74:77], v[64:65], off nt
	global_load_dwordx4 v[78:81], v[132:133], off offset:512 nt
	global_load_dwordx4 v[82:85], v[132:133], off offset:528 nt
	global_load_dwordx4 v[104:107], v[64:65], off offset:256 nt
	v_add_u32_e32 v64, 0x90, v208
	v_ashrrev_i32_e32 v65, 31, v64
	v_lshl_add_u64 v[108:109], v[64:65], 3, s[12:13]
	global_load_dwordx2 v[134:135], v[108:109], off
	v_lshlrev_b64 v[108:109], 12, v[64:65]
	v_lshl_add_u64 v[108:109], s[6:7], 0, v[108:109]
	v_lshlrev_b64 v[64:65], 11, v[64:65]
	v_lshl_add_u64 v[116:117], s[10:11], 0, v[64:65]
	v_lshl_add_u64 v[64:65], v[108:109], 0, v[206:207]
	global_load_dwordx4 v[108:111], v[64:65], off nt
	global_load_dwordx4 v[112:115], v[64:65], off offset:16 nt
	v_lshl_add_u64 v[128:129], v[116:117], 0, v[210:211]
	global_load_dwordx4 v[116:119], v[128:129], off nt
	global_load_dwordx4 v[120:123], v[64:65], off offset:512 nt
	global_load_dwordx4 v[124:127], v[64:65], off offset:528 nt
	s_nop 0
	global_load_dwordx4 v[128:131], v[128:129], off offset:256 nt
	s_waitcnt vmcnt(0) lgkmcnt(0)
	v_sub_f32_e32 v69, v69, v86
	v_sub_f32_e32 v68, v68, v86
	v_sub_f32_e32 v67, v67, v86
	v_sub_f32_e32 v66, v66, v86
	v_pk_mul_f32 v[66:67], v[86:87], v[66:67] op_sel:[1,0]
	v_pk_mul_f32 v[68:69], v[86:87], v[68:69] op_sel:[1,0]
	v_pk_fma_f32 v[60:61], v[204:205], v[66:67], v[60:61]
	v_pk_fma_f32 v[62:63], v[202:203], v[68:69], v[62:63]
	v_sub_f32_e32 v67, v73, v86
	v_sub_f32_e32 v66, v72, v86
	v_sub_f32_e32 v69, v71, v86
	v_sub_f32_e32 v68, v70, v86
	v_pk_mul_f32 v[68:69], v[86:87], v[68:69] op_sel:[1,0]
	v_pk_mul_f32 v[66:67], v[86:87], v[66:67] op_sel:[1,0]
	v_pk_fma_f32 v[56:57], v[200:201], v[68:69], v[56:57]
	v_pk_fma_f32 v[58:59], v[198:199], v[66:67], v[58:59]
	v_pk_fma_f32 v[62:63], v[102:103], s[30:31], v[62:63] op_sel_hi:[1,0,1]
	v_pk_fma_f32 v[60:61], v[100:101], s[30:31], v[60:61] op_sel_hi:[1,0,1]
	v_pk_fma_f32 v[66:67], v[98:99], s[30:31], v[58:59] op_sel_hi:[1,0,1]
	v_pk_fma_f32 v[68:69], v[96:97], s[30:31], v[56:57] op_sel_hi:[1,0,1]
	v_lshlrev_b32_e32 v56, 16, v74
	v_and_b32_e32 v57, 0xffff0000, v74
	v_lshlrev_b32_e32 v58, 16, v75
	v_and_b32_e32 v59, 0xffff0000, v75
	v_pk_add_f32 v[56:57], v[60:61], v[56:57]
	v_pk_add_f32 v[58:59], v[62:63], v[58:59]
	v_lshlrev_b32_e32 v60, 16, v76
	v_and_b32_e32 v61, 0xffff0000, v76
	v_lshlrev_b32_e32 v62, 16, v77
	v_and_b32_e32 v63, 0xffff0000, v77
	v_pk_add_f32 v[60:61], v[68:69], v[60:61]
	v_pk_add_f32 v[62:63], v[66:67], v[62:63]
	global_store_dwordx4 v[132:133], v[56:59], off
	global_store_dwordx4 v[132:133], v[60:63], off offset:16
	s_nop 0
	v_sub_f32_e32 v57, v81, v86
	v_sub_f32_e32 v56, v80, v86
	v_sub_f32_e32 v59, v79, v86
	v_sub_f32_e32 v58, v78, v86
	v_pk_mul_f32 v[58:59], v[86:87], v[58:59] op_sel:[1,0]
	v_pk_mul_f32 v[56:57], v[86:87], v[56:57] op_sel:[1,0]
	v_pk_fma_f32 v[52:53], v[196:197], v[58:59], v[52:53]
	v_pk_fma_f32 v[54:55], v[194:195], v[56:57], v[54:55]
	v_sub_f32_e32 v57, v85, v86
	v_sub_f32_e32 v56, v84, v86
	v_sub_f32_e32 v59, v83, v86
	v_sub_f32_e32 v58, v82, v86
	v_pk_mul_f32 v[58:59], v[86:87], v[58:59] op_sel:[1,0]
	v_pk_mul_f32 v[56:57], v[86:87], v[56:57] op_sel:[1,0]
	v_pk_fma_f32 v[48:49], v[192:193], v[58:59], v[48:49]
	v_pk_fma_f32 v[50:51], v[190:191], v[56:57], v[50:51]
	v_pk_fma_f32 v[54:55], v[94:95], s[30:31], v[54:55] op_sel_hi:[1,0,1]
	v_pk_fma_f32 v[52:53], v[92:93], s[30:31], v[52:53] op_sel_hi:[1,0,1]
	v_pk_fma_f32 v[56:57], v[90:91], s[30:31], v[50:51] op_sel_hi:[1,0,1]
	v_pk_fma_f32 v[58:59], v[88:89], s[30:31], v[48:49] op_sel_hi:[1,0,1]
	v_lshlrev_b32_e32 v48, 16, v104
	v_and_b32_e32 v49, 0xffff0000, v104
	v_lshlrev_b32_e32 v50, 16, v105
	v_and_b32_e32 v51, 0xffff0000, v105
	v_pk_add_f32 v[48:49], v[52:53], v[48:49]
	v_pk_add_f32 v[50:51], v[54:55], v[50:51]
	v_lshlrev_b32_e32 v52, 16, v106
	v_and_b32_e32 v53, 0xffff0000, v106
	v_lshlrev_b32_e32 v54, 16, v107
	v_and_b32_e32 v55, 0xffff0000, v107
	v_pk_add_f32 v[52:53], v[58:59], v[52:53]
	v_pk_add_f32 v[54:55], v[56:57], v[54:55]
	global_store_dwordx4 v[132:133], v[48:51], off offset:512
	global_store_dwordx4 v[132:133], v[52:55], off offset:528
	s_nop 0
	v_sub_f32_e32 v49, v111, v134
	v_sub_f32_e32 v48, v110, v134
	v_sub_f32_e32 v51, v109, v134
	v_sub_f32_e32 v50, v108, v134
	v_pk_mul_f32 v[50:51], v[134:135], v[50:51] op_sel:[1,0]
	v_pk_mul_f32 v[48:49], v[134:135], v[48:49] op_sel:[1,0]
	v_pk_fma_f32 v[44:45], v[204:205], v[50:51], v[44:45]
	v_pk_fma_f32 v[46:47], v[202:203], v[48:49], v[46:47]
	v_sub_f32_e32 v49, v115, v134
	v_sub_f32_e32 v48, v114, v134
	v_sub_f32_e32 v51, v113, v134
	v_sub_f32_e32 v50, v112, v134
	v_pk_mul_f32 v[50:51], v[134:135], v[50:51] op_sel:[1,0]
	v_pk_mul_f32 v[48:49], v[134:135], v[48:49] op_sel:[1,0]
	v_pk_fma_f32 v[40:41], v[200:201], v[50:51], v[40:41]
	v_pk_fma_f32 v[42:43], v[198:199], v[48:49], v[42:43]
	v_pk_fma_f32 v[46:47], v[102:103], s[30:31], v[46:47] op_sel_hi:[1,0,1]
	v_pk_fma_f32 v[44:45], v[100:101], s[30:31], v[44:45] op_sel_hi:[1,0,1]
	v_pk_fma_f32 v[48:49], v[98:99], s[30:31], v[42:43] op_sel_hi:[1,0,1]
	v_pk_fma_f32 v[50:51], v[96:97], s[30:31], v[40:41] op_sel_hi:[1,0,1]
	v_lshlrev_b32_e32 v40, 16, v116
	v_and_b32_e32 v41, 0xffff0000, v116
	v_lshlrev_b32_e32 v42, 16, v117
	v_and_b32_e32 v43, 0xffff0000, v117
	v_pk_add_f32 v[40:41], v[44:45], v[40:41]
	v_pk_add_f32 v[42:43], v[46:47], v[42:43]
	v_lshlrev_b32_e32 v44, 16, v118
	v_and_b32_e32 v45, 0xffff0000, v118
	v_lshlrev_b32_e32 v46, 16, v119
	v_and_b32_e32 v47, 0xffff0000, v119
	v_pk_add_f32 v[44:45], v[50:51], v[44:45]
	v_pk_add_f32 v[46:47], v[48:49], v[46:47]
	global_store_dwordx4 v[64:65], v[40:43], off
	global_store_dwordx4 v[64:65], v[44:47], off offset:16
	s_nop 0
	v_sub_f32_e32 v41, v123, v134
	v_sub_f32_e32 v40, v122, v134
	v_sub_f32_e32 v43, v121, v134
	v_sub_f32_e32 v42, v120, v134
	v_pk_mul_f32 v[42:43], v[134:135], v[42:43] op_sel:[1,0]
	v_pk_mul_f32 v[40:41], v[134:135], v[40:41] op_sel:[1,0]
	v_pk_fma_f32 v[36:37], v[196:197], v[42:43], v[36:37]
	v_pk_fma_f32 v[38:39], v[194:195], v[40:41], v[38:39]
	v_sub_f32_e32 v41, v127, v134
	v_sub_f32_e32 v40, v126, v134
	v_sub_f32_e32 v43, v125, v134
	v_sub_f32_e32 v42, v124, v134
	v_pk_mul_f32 v[42:43], v[134:135], v[42:43] op_sel:[1,0]
	v_pk_mul_f32 v[40:41], v[134:135], v[40:41] op_sel:[1,0]
	v_pk_fma_f32 v[32:33], v[192:193], v[42:43], v[32:33]
	v_pk_fma_f32 v[34:35], v[190:191], v[40:41], v[34:35]
	v_pk_fma_f32 v[38:39], v[94:95], s[30:31], v[38:39] op_sel_hi:[1,0,1]
	v_pk_fma_f32 v[36:37], v[92:93], s[30:31], v[36:37] op_sel_hi:[1,0,1]
	v_pk_fma_f32 v[40:41], v[90:91], s[30:31], v[34:35] op_sel_hi:[1,0,1]
	v_pk_fma_f32 v[42:43], v[88:89], s[30:31], v[32:33] op_sel_hi:[1,0,1]
	v_lshlrev_b32_e32 v32, 16, v128
	v_and_b32_e32 v33, 0xffff0000, v128
	v_lshlrev_b32_e32 v34, 16, v129
	v_and_b32_e32 v35, 0xffff0000, v129
	v_pk_add_f32 v[32:33], v[36:37], v[32:33]
	v_pk_add_f32 v[34:35], v[38:39], v[34:35]
	v_lshlrev_b32_e32 v36, 16, v130
	v_and_b32_e32 v37, 0xffff0000, v130
	v_lshlrev_b32_e32 v38, 16, v131
	v_and_b32_e32 v39, 0xffff0000, v131
	v_pk_add_f32 v[36:37], v[42:43], v[36:37]
	v_pk_add_f32 v[38:39], v[40:41], v[38:39]
	global_store_dwordx4 v[64:65], v[32:35], off offset:512
	global_store_dwordx4 v[64:65], v[36:39], off offset:528
	s_nop 0
	v_add_u32_e32 v32, 0xa0, v208
	v_ashrrev_i32_e32 v33, 31, v32
	v_lshl_add_u64 v[34:35], v[32:33], 3, s[12:13]
	global_load_dwordx2 v[82:83], v[34:35], off
	v_lshlrev_b64 v[34:35], 12, v[32:33]
	v_lshl_add_u64 v[34:35], s[6:7], 0, v[34:35]
	v_lshl_add_u64 v[84:85], v[34:35], 0, v[206:207]
	global_load_dwordx4 v[34:37], v[84:85], off nt
	global_load_dwordx4 v[38:41], v[84:85], off offset:16 nt
	v_lshlrev_b64 v[32:33], 11, v[32:33]
	v_lshl_add_u64 v[32:33], s[10:11], 0, v[32:33]
	v_lshl_add_u64 v[32:33], v[32:33], 0, v[210:211]
	global_load_dwordx4 v[42:45], v[32:33], off nt
	global_load_dwordx4 v[46:49], v[84:85], off offset:512 nt
	global_load_dwordx4 v[50:53], v[84:85], off offset:528 nt
	global_load_dwordx4 v[54:57], v[32:33], off offset:256 nt
	v_add_u32_e32 v32, 0xb0, v208
	v_ashrrev_i32_e32 v33, 31, v32
	v_lshl_add_u64 v[58:59], v[32:33], 3, s[12:13]
	global_load_dwordx2 v[86:87], v[58:59], off
	v_lshlrev_b64 v[58:59], 12, v[32:33]
	v_lshl_add_u64 v[58:59], s[6:7], 0, v[58:59]
	v_lshlrev_b64 v[32:33], 11, v[32:33]
	v_lshl_add_u64 v[66:67], s[10:11], 0, v[32:33]
	v_lshl_add_u64 v[32:33], v[58:59], 0, v[206:207]
	global_load_dwordx4 v[58:61], v[32:33], off nt
	global_load_dwordx4 v[62:65], v[32:33], off offset:16 nt
	v_lshl_add_u64 v[78:79], v[66:67], 0, v[210:211]
	global_load_dwordx4 v[66:69], v[78:79], off nt
	global_load_dwordx4 v[70:73], v[32:33], off offset:512 nt
	global_load_dwordx4 v[74:77], v[32:33], off offset:528 nt
	s_nop 0
	global_load_dwordx4 v[78:81], v[78:79], off offset:256 nt
	s_waitcnt vmcnt(0) lgkmcnt(0)
	v_sub_f32_e32 v37, v37, v82
	v_sub_f32_e32 v36, v36, v82
	v_sub_f32_e32 v35, v35, v82
	v_sub_f32_e32 v34, v34, v82
	v_pk_mul_f32 v[34:35], v[82:83], v[34:35] op_sel:[1,0]
	v_pk_mul_f32 v[36:37], v[82:83], v[36:37] op_sel:[1,0]
	v_pk_fma_f32 v[28:29], v[204:205], v[34:35], v[28:29]
	v_pk_fma_f32 v[30:31], v[202:203], v[36:37], v[30:31]
	v_sub_f32_e32 v35, v41, v82
	v_sub_f32_e32 v34, v40, v82
	v_sub_f32_e32 v37, v39, v82
	v_sub_f32_e32 v36, v38, v82
	v_pk_mul_f32 v[36:37], v[82:83], v[36:37] op_sel:[1,0]
	v_pk_mul_f32 v[34:35], v[82:83], v[34:35] op_sel:[1,0]
	v_pk_fma_f32 v[24:25], v[200:201], v[36:37], v[24:25]
	v_pk_fma_f32 v[26:27], v[198:199], v[34:35], v[26:27]
	v_pk_fma_f32 v[30:31], v[102:103], s[30:31], v[30:31] op_sel_hi:[1,0,1]
	v_pk_fma_f32 v[28:29], v[100:101], s[30:31], v[28:29] op_sel_hi:[1,0,1]
	v_pk_fma_f32 v[34:35], v[98:99], s[30:31], v[26:27] op_sel_hi:[1,0,1]
	v_pk_fma_f32 v[36:37], v[96:97], s[30:31], v[24:25] op_sel_hi:[1,0,1]
	v_lshlrev_b32_e32 v24, 16, v42
	v_and_b32_e32 v25, 0xffff0000, v42
	v_lshlrev_b32_e32 v26, 16, v43
	v_and_b32_e32 v27, 0xffff0000, v43
	v_pk_add_f32 v[24:25], v[28:29], v[24:25]
	v_pk_add_f32 v[26:27], v[30:31], v[26:27]
	v_lshlrev_b32_e32 v28, 16, v44
	v_and_b32_e32 v29, 0xffff0000, v44
	v_lshlrev_b32_e32 v30, 16, v45
	v_and_b32_e32 v31, 0xffff0000, v45
	v_pk_add_f32 v[28:29], v[36:37], v[28:29]
	v_pk_add_f32 v[30:31], v[34:35], v[30:31]
	global_store_dwordx4 v[84:85], v[24:27], off
	global_store_dwordx4 v[84:85], v[28:31], off offset:16
	s_nop 0
	v_sub_f32_e32 v25, v49, v82
	v_sub_f32_e32 v24, v48, v82
	v_sub_f32_e32 v27, v47, v82
	v_sub_f32_e32 v26, v46, v82
	v_pk_mul_f32 v[26:27], v[82:83], v[26:27] op_sel:[1,0]
	v_pk_mul_f32 v[24:25], v[82:83], v[24:25] op_sel:[1,0]
	v_pk_fma_f32 v[20:21], v[196:197], v[26:27], v[20:21]
	v_pk_fma_f32 v[22:23], v[194:195], v[24:25], v[22:23]
	v_sub_f32_e32 v25, v53, v82
	v_sub_f32_e32 v24, v52, v82
	v_sub_f32_e32 v27, v51, v82
	v_sub_f32_e32 v26, v50, v82
	v_pk_mul_f32 v[26:27], v[82:83], v[26:27] op_sel:[1,0]
	v_pk_mul_f32 v[24:25], v[82:83], v[24:25] op_sel:[1,0]
	v_pk_fma_f32 v[16:17], v[192:193], v[26:27], v[16:17]
	v_pk_fma_f32 v[18:19], v[190:191], v[24:25], v[18:19]
	v_pk_fma_f32 v[22:23], v[94:95], s[30:31], v[22:23] op_sel_hi:[1,0,1]
	v_pk_fma_f32 v[20:21], v[92:93], s[30:31], v[20:21] op_sel_hi:[1,0,1]
	v_pk_fma_f32 v[24:25], v[90:91], s[30:31], v[18:19] op_sel_hi:[1,0,1]
	v_pk_fma_f32 v[26:27], v[88:89], s[30:31], v[16:17] op_sel_hi:[1,0,1]
	v_lshlrev_b32_e32 v16, 16, v54
	v_and_b32_e32 v17, 0xffff0000, v54
	v_lshlrev_b32_e32 v18, 16, v55
	v_and_b32_e32 v19, 0xffff0000, v55
	v_pk_add_f32 v[16:17], v[20:21], v[16:17]
	v_pk_add_f32 v[18:19], v[22:23], v[18:19]
	v_lshlrev_b32_e32 v20, 16, v56
	v_and_b32_e32 v21, 0xffff0000, v56
	v_lshlrev_b32_e32 v22, 16, v57
	v_and_b32_e32 v23, 0xffff0000, v57
	v_pk_add_f32 v[20:21], v[26:27], v[20:21]
	v_pk_add_f32 v[22:23], v[24:25], v[22:23]
	global_store_dwordx4 v[84:85], v[16:19], off offset:512
	global_store_dwordx4 v[84:85], v[20:23], off offset:528
	s_nop 0
	v_sub_f32_e32 v17, v61, v86
	v_sub_f32_e32 v16, v60, v86
	v_sub_f32_e32 v19, v59, v86
	v_sub_f32_e32 v18, v58, v86
	v_pk_mul_f32 v[18:19], v[86:87], v[18:19] op_sel:[1,0]
	v_pk_mul_f32 v[16:17], v[86:87], v[16:17] op_sel:[1,0]
	v_pk_fma_f32 v[12:13], v[204:205], v[18:19], v[12:13]
	v_pk_fma_f32 v[14:15], v[202:203], v[16:17], v[14:15]
	v_sub_f32_e32 v17, v65, v86
	v_sub_f32_e32 v16, v64, v86
	v_sub_f32_e32 v19, v63, v86
	v_sub_f32_e32 v18, v62, v86
	v_pk_mul_f32 v[18:19], v[86:87], v[18:19] op_sel:[1,0]
	v_pk_mul_f32 v[16:17], v[86:87], v[16:17] op_sel:[1,0]
	v_pk_fma_f32 v[8:9], v[200:201], v[18:19], v[8:9]
	v_pk_fma_f32 v[10:11], v[198:199], v[16:17], v[10:11]
	v_pk_fma_f32 v[14:15], v[102:103], s[30:31], v[14:15] op_sel_hi:[1,0,1]
	v_pk_fma_f32 v[12:13], v[100:101], s[30:31], v[12:13] op_sel_hi:[1,0,1]
	v_pk_fma_f32 v[16:17], v[98:99], s[30:31], v[10:11] op_sel_hi:[1,0,1]
	v_pk_fma_f32 v[18:19], v[96:97], s[30:31], v[8:9] op_sel_hi:[1,0,1]
	v_lshlrev_b32_e32 v8, 16, v66
	v_and_b32_e32 v9, 0xffff0000, v66
	v_lshlrev_b32_e32 v10, 16, v67
	v_and_b32_e32 v11, 0xffff0000, v67
	v_pk_add_f32 v[8:9], v[12:13], v[8:9]
	v_pk_add_f32 v[10:11], v[14:15], v[10:11]
	v_lshlrev_b32_e32 v12, 16, v68
	v_and_b32_e32 v13, 0xffff0000, v68
	v_lshlrev_b32_e32 v14, 16, v69
	v_and_b32_e32 v15, 0xffff0000, v69
	v_pk_add_f32 v[12:13], v[18:19], v[12:13]
	v_pk_add_f32 v[14:15], v[16:17], v[14:15]
	global_store_dwordx4 v[32:33], v[8:11], off
	global_store_dwordx4 v[32:33], v[12:15], off offset:16
	s_nop 0
	v_sub_f32_e32 v9, v73, v86
	v_sub_f32_e32 v8, v72, v86
	v_sub_f32_e32 v11, v71, v86
	v_sub_f32_e32 v10, v70, v86
	v_pk_mul_f32 v[10:11], v[86:87], v[10:11] op_sel:[1,0]
	v_pk_mul_f32 v[8:9], v[86:87], v[8:9] op_sel:[1,0]
	v_pk_fma_f32 v[4:5], v[196:197], v[10:11], v[4:5]
	v_pk_fma_f32 v[6:7], v[194:195], v[8:9], v[6:7]
	v_sub_f32_e32 v9, v77, v86
	v_sub_f32_e32 v8, v76, v86
	v_sub_f32_e32 v11, v75, v86
	v_sub_f32_e32 v10, v74, v86
	v_pk_mul_f32 v[10:11], v[86:87], v[10:11] op_sel:[1,0]
	v_pk_mul_f32 v[8:9], v[86:87], v[8:9] op_sel:[1,0]
	v_pk_fma_f32 v[0:1], v[192:193], v[10:11], v[0:1]
	v_pk_fma_f32 v[2:3], v[190:191], v[8:9], v[2:3]
	v_pk_fma_f32 v[6:7], v[94:95], s[30:31], v[6:7] op_sel_hi:[1,0,1]
	v_pk_fma_f32 v[4:5], v[92:93], s[30:31], v[4:5] op_sel_hi:[1,0,1]
	v_pk_fma_f32 v[8:9], v[90:91], s[30:31], v[2:3] op_sel_hi:[1,0,1]
	v_pk_fma_f32 v[10:11], v[88:89], s[30:31], v[0:1] op_sel_hi:[1,0,1]
	v_lshlrev_b32_e32 v0, 16, v78
	v_and_b32_e32 v1, 0xffff0000, v78
	v_lshlrev_b32_e32 v2, 16, v79
	v_and_b32_e32 v3, 0xffff0000, v79
	v_pk_add_f32 v[0:1], v[4:5], v[0:1]
	v_pk_add_f32 v[2:3], v[6:7], v[2:3]
	v_lshlrev_b32_e32 v4, 16, v80
	v_and_b32_e32 v5, 0xffff0000, v80
	v_lshlrev_b32_e32 v6, 16, v81
	v_and_b32_e32 v7, 0xffff0000, v81
	v_pk_add_f32 v[4:5], v[10:11], v[4:5]
	v_pk_add_f32 v[6:7], v[8:9], v[6:7]
	global_store_dwordx4 v[32:33], v[0:3], off offset:512
	global_store_dwordx4 v[32:33], v[4:7], off offset:528
	s_cbranch_vccnz .LBB0_1484
	s_andn2_b64 vcc, exec, s[8:9]
	s_cbranch_vccnz .LBB0_1483
	s_barrier
	s_branch .LBB0_1483
